# no setprio flips, 64B-aligned K-loop heads, hand-written conv LN tail, hand-written SwiGLU epilogues (P1,P10)
# speedup vs baseline: 1.0084x; 1.0064x over previous
; __device__ __forceinline__ void load_rstd(const float* part, int row0, int fq, float (&rs)[2][4]) {
; #pragma unroll
;     for (int ai = 0; ai < 2; ++ai)
; #pragma unroll
;         for (int m = 0; m < 4; ++m) { const float* p = part + (size_t)(row0 + ai * HALF + m * 16) * NPART + fq * 8;
;             const f32x4 a = *(const f32x4*)p, b = *(const f32x4*)(p + 4); float s = ((a[0] + a[1]) + (a[2] + a[3])) + ((b[0] + b[1]) + (b[2] + b[3]));
;             s += __shfl_xor(s, 16); s += __shfl_xor(s, 32); rs[ai][m] = rsqrtf(s * (1.0f / D) + RMS_EPS); }
;     __device__ __forceinline__ void operator()(const f32x4 (&acc)[2][2][4][2], const Unit& u, int wr, int wc, int fr, int fq) const {
;         const int row0 = u.pm * BM + wr * 64 + fr, col0 = u.pn * HALF + wc * 32 + 8 * fq;
;         float rs[2][4]; load_rstd(part, row0, fq, rs);
; #pragma unroll
;         for (int ai = 0; ai < 2; ++ai)
; #pragma unroll
;             for (int m = 0; m < 4; ++m) { const float sc = rs[ai][m]; f32x4 o[2];
; #pragma unroll
;                 for (int n = 0; n < 2; ++n) { const f32x4 g = acc[ai][0][m][n] * sc, up = acc[ai][1][m][n] * sc;
.LBB0_264:
	v_lshl_add_u32 v249, s11, 8, v192
	s_mov_b64 vcc, 0x1000
	s_mov_b64 s[100:101], 0x4000
	v_ashrrev_i32_e32 v179, 31, v249
	v_mov_b32_e32 v178, v249
	v_lshlrev_b64 v[178:179], 7, v[178:179]
	v_lshl_add_u64 v[178:179], v[152:153], 0, v[178:179]
	v_lshl_add_u64 v[234:235], v[178:179], 0, vcc
	v_lshl_add_u64 v[236:237], v[178:179], 0, s[100:101]
	v_lshl_add_u64 v[238:239], v[236:237], 0, vcc
	global_load_dwordx4 v[128:131], v[178:179], off
	global_load_dwordx4 v[132:135], v[178:179], off offset:16
	global_load_dwordx4 v[136:139], v[178:179], off offset:2048
	global_load_dwordx4 v[140:143], v[178:179], off offset:2064
	global_load_dwordx4 v[162:165], v[234:235], off
	global_load_dwordx4 v[166:169], v[234:235], off offset:16
	global_load_dwordx4 v[170:173], v[234:235], off offset:2048
	global_load_dwordx4 v[174:177], v[234:235], off offset:2064
	global_load_dwordx4 v[200:203], v[236:237], off
	global_load_dwordx4 v[204:207], v[236:237], off offset:16
	global_load_dwordx4 v[208:211], v[236:237], off offset:2048
	global_load_dwordx4 v[212:215], v[236:237], off offset:2064
	global_load_dwordx4 v[216:219], v[238:239], off
	global_load_dwordx4 v[222:225], v[238:239], off offset:16
	global_load_dwordx4 v[226:229], v[238:239], off offset:2048
	global_load_dwordx4 v[230:233], v[238:239], off offset:2064
	v_mov_b32_e32 v248, 0xbfb8aa3b
	v_mov_b32_e32 v250, 0x358637bd
	v_lshl_or_b32 v251, s92, 7, v194
	v_lshlrev_b32_e32 v251, 1, v251
	v_mul_u32_u24_e32 v249, 0x2c00, v249
	v_add_u32_e32 v251, v251, v249
	s_waitcnt vmcnt(0)
	v_add_f32_e32 v128, v128, v129
	v_add_f32_e32 v130, v130, v131
	v_add_f32_e32 v132, v132, v133
	v_add_f32_e32 v134, v134, v135
	v_add_f32_e32 v136, v136, v137
	v_add_f32_e32 v138, v138, v139
	v_add_f32_e32 v140, v140, v141
	v_add_f32_e32 v142, v142, v143
	v_add_f32_e32 v162, v162, v163
	v_add_f32_e32 v164, v164, v165
	v_add_f32_e32 v166, v166, v167
	v_add_f32_e32 v168, v168, v169
	v_add_f32_e32 v170, v170, v171
	v_add_f32_e32 v172, v172, v173
	v_add_f32_e32 v174, v174, v175
	v_add_f32_e32 v176, v176, v177
	v_add_f32_e32 v200, v200, v201
	v_add_f32_e32 v202, v202, v203
	v_add_f32_e32 v204, v204, v205
	v_add_f32_e32 v206, v206, v207
	v_add_f32_e32 v208, v208, v209
	v_add_f32_e32 v210, v210, v211
	v_add_f32_e32 v212, v212, v213
	v_add_f32_e32 v214, v214, v215
	v_add_f32_e32 v216, v216, v217
	v_add_f32_e32 v218, v218, v219
	v_add_f32_e32 v222, v222, v223
	v_add_f32_e32 v224, v224, v225
	v_add_f32_e32 v226, v226, v227
	v_add_f32_e32 v228, v228, v229
	v_add_f32_e32 v230, v230, v231
	v_add_f32_e32 v232, v232, v233
	v_add_f32_e32 v128, v128, v130
	v_add_f32_e32 v132, v132, v134
	v_add_f32_e32 v136, v136, v138
	v_add_f32_e32 v140, v140, v142
	v_add_f32_e32 v162, v162, v164
	v_add_f32_e32 v166, v166, v168
	v_add_f32_e32 v170, v170, v172
	v_add_f32_e32 v174, v174, v176
	v_add_f32_e32 v200, v200, v202
	v_add_f32_e32 v204, v204, v206
	v_add_f32_e32 v208, v208, v210
	v_add_f32_e32 v212, v212, v214
	v_add_f32_e32 v216, v216, v218
	v_add_f32_e32 v222, v222, v224
	v_add_f32_e32 v226, v226, v228
	v_add_f32_e32 v230, v230, v232
	v_add_f32_e32 v128, v128, v132
	v_add_f32_e32 v136, v136, v140
	v_add_f32_e32 v162, v162, v166
	v_add_f32_e32 v170, v170, v174
	v_add_f32_e32 v200, v200, v204
	v_add_f32_e32 v208, v208, v212
	v_add_f32_e32 v216, v216, v222
	v_add_f32_e32 v226, v226, v230
	v_mov_b32_e32 v179, v128
	v_mov_b32_e32 v235, v136
	v_mov_b32_e32 v237, v162
	v_mov_b32_e32 v239, v170
	v_mov_b32_e32 v241, v200
	v_mov_b32_e32 v243, v208
	v_mov_b32_e32 v245, v216
	v_mov_b32_e32 v247, v226
	s_nop 1
	v_permlane16_swap_b32_e32 v128, v179
	v_permlane16_swap_b32_e32 v136, v235
	v_permlane16_swap_b32_e32 v162, v237
	v_permlane16_swap_b32_e32 v170, v239
	v_permlane16_swap_b32_e32 v200, v241
	v_permlane16_swap_b32_e32 v208, v243
	v_permlane16_swap_b32_e32 v216, v245
	v_permlane16_swap_b32_e32 v226, v247
	v_add_f32_e32 v128, v128, v179
	v_add_f32_e32 v136, v136, v235
	v_add_f32_e32 v162, v162, v237
	v_add_f32_e32 v170, v170, v239
	v_add_f32_e32 v200, v200, v241
	v_add_f32_e32 v208, v208, v243
	v_add_f32_e32 v216, v216, v245
	v_add_f32_e32 v226, v226, v247
	v_mov_b32_e32 v179, v128
	v_mov_b32_e32 v235, v136
	v_mov_b32_e32 v237, v162
	v_mov_b32_e32 v239, v170
	v_mov_b32_e32 v241, v200
	v_mov_b32_e32 v243, v208
	v_mov_b32_e32 v245, v216
	v_mov_b32_e32 v247, v226
	s_nop 1
	v_permlane32_swap_b32_e32 v128, v179
	v_permlane32_swap_b32_e32 v136, v235
	v_permlane32_swap_b32_e32 v162, v237
	v_permlane32_swap_b32_e32 v170, v239
	v_permlane32_swap_b32_e32 v200, v241
	v_permlane32_swap_b32_e32 v208, v243
	v_permlane32_swap_b32_e32 v216, v245
	v_permlane32_swap_b32_e32 v226, v247
	v_add_f32_e32 v128, v128, v179
	v_add_f32_e32 v136, v136, v235
	v_add_f32_e32 v162, v162, v237
	v_add_f32_e32 v170, v170, v239
	v_add_f32_e32 v200, v200, v241
	v_add_f32_e32 v208, v208, v243
	v_add_f32_e32 v216, v216, v245
	v_add_f32_e32 v226, v226, v247
	v_fmamk_f32 v178, v128, 0x3a000000, v250
	v_fmamk_f32 v234, v136, 0x3a000000, v250
	v_fmamk_f32 v236, v162, 0x3a000000, v250
	v_fmamk_f32 v238, v170, 0x3a000000, v250
	v_fmamk_f32 v240, v200, 0x3a000000, v250
	v_fmamk_f32 v242, v208, 0x3a000000, v250
	v_fmamk_f32 v244, v216, 0x3a000000, v250
	v_fmamk_f32 v246, v226, 0x3a000000, v250
	v_rsq_f32_e32 v178, v178
	v_rsq_f32_e32 v234, v234
	v_rsq_f32_e32 v236, v236
	v_rsq_f32_e32 v238, v238
	v_rsq_f32_e32 v240, v240
	v_rsq_f32_e32 v242, v242
	v_rsq_f32_e32 v244, v244
	v_rsq_f32_e32 v246, v246
	v_pk_mul_f32 v[124:125], v[124:125], v[178:179] op_sel_hi:[1,0]
	v_pk_mul_f32 v[126:127], v[126:127], v[178:179] op_sel_hi:[1,0]
	v_pk_mul_f32 v[116:117], v[116:117], v[178:179] op_sel_hi:[1,0]
; __device__ __forceinline__ unsigned cvt_pk_bf16(float lo, float hi) { unsigned r; asm volatile("v_cvt_pk_bf16_f32 %0, %1, %2" : "=v"(r) : "v"(lo), "v"(hi)); return r; }
; __device__ __forceinline__ float sigmoidf_(float x) { return fast_rcp(1.0f + fast_exp2(-1.4426950408889634f * x)); }
;     __device__ __forceinline__ void operator()(const f32x4 (&acc)[2][2][4][2], const Unit& u, int wr, int wc, int fr, int fq) const {
;     ...
;             for (int m = 0; m < 4; ++m) { const float sc = rs[ai][m]; f32x4 o[2];
; #pragma unroll
;                 for (int n = 0; n < 2; ++n) { const f32x4 g = acc[ai][0][m][n] * sc, up = acc[ai][1][m][n] * sc;
; #pragma unroll
;                     for (int e = 0; e < 4; ++e) o[n][e] = g[e] * sigmoidf_(g[e]) * up[e]; }
;                 u32x4 w; w.x = cvt_pk_bf16(o[0][0], o[0][1]); w.y = cvt_pk_bf16(o[0][2], o[0][3]); w.z = cvt_pk_bf16(o[1][0], o[1][1]); w.w = cvt_pk_bf16(o[1][2], o[1][3]);
;                 *(u32x4*)(O + (size_t)(row0 + ai * HALF + m * 16) * FF + col0) = w; }
	v_pk_mul_f32 v[118:119], v[118:119], v[178:179] op_sel_hi:[1,0]
	v_pk_mul_f32 v[108:109], v[108:109], v[234:235] op_sel_hi:[1,0]
	v_pk_mul_f32 v[110:111], v[110:111], v[234:235] op_sel_hi:[1,0]
	v_pk_mul_f32 v[100:101], v[100:101], v[234:235] op_sel_hi:[1,0]
	v_pk_mul_f32 v[102:103], v[102:103], v[234:235] op_sel_hi:[1,0]
	v_pk_mul_f32 v[128:129], v[124:125], v[248:249] op_sel_hi:[1,0]
	v_pk_mul_f32 v[130:131], v[126:127], v[248:249] op_sel_hi:[1,0]
	v_pk_mul_f32 v[132:133], v[116:117], v[248:249] op_sel_hi:[1,0]
	v_pk_mul_f32 v[134:135], v[118:119], v[248:249] op_sel_hi:[1,0]
	v_pk_mul_f32 v[162:163], v[108:109], v[248:249] op_sel_hi:[1,0]
	v_pk_mul_f32 v[164:165], v[110:111], v[248:249] op_sel_hi:[1,0]
	v_pk_mul_f32 v[166:167], v[100:101], v[248:249] op_sel_hi:[1,0]
	v_pk_mul_f32 v[168:169], v[102:103], v[248:249] op_sel_hi:[1,0]
	v_exp_f32_e32 v128, v128
	v_exp_f32_e32 v129, v129
	v_exp_f32_e32 v130, v130
	v_exp_f32_e32 v131, v131
	v_exp_f32_e32 v132, v132
	v_exp_f32_e32 v133, v133
	v_exp_f32_e32 v134, v134
	v_exp_f32_e32 v135, v135
	v_exp_f32_e32 v162, v162
	v_exp_f32_e32 v163, v163
	v_exp_f32_e32 v164, v164
	v_exp_f32_e32 v165, v165
	v_exp_f32_e32 v166, v166
	v_exp_f32_e32 v167, v167
	v_exp_f32_e32 v168, v168
	v_exp_f32_e32 v169, v169
	v_pk_mul_f32 v[120:121], v[120:121], v[178:179] op_sel_hi:[1,0]
	v_pk_mul_f32 v[122:123], v[122:123], v[178:179] op_sel_hi:[1,0]
	v_pk_mul_f32 v[112:113], v[112:113], v[178:179] op_sel_hi:[1,0]
	v_pk_mul_f32 v[114:115], v[114:115], v[178:179] op_sel_hi:[1,0]
	v_pk_mul_f32 v[104:105], v[104:105], v[234:235] op_sel_hi:[1,0]
	v_pk_mul_f32 v[106:107], v[106:107], v[234:235] op_sel_hi:[1,0]
	v_pk_mul_f32 v[96:97], v[96:97], v[234:235] op_sel_hi:[1,0]
	v_pk_mul_f32 v[98:99], v[98:99], v[234:235] op_sel_hi:[1,0]
	v_pk_add_f32 v[128:129], v[128:129], 1.0 op_sel_hi:[1,0]
	v_pk_add_f32 v[130:131], v[130:131], 1.0 op_sel_hi:[1,0]
	v_pk_add_f32 v[132:133], v[132:133], 1.0 op_sel_hi:[1,0]
	v_pk_add_f32 v[134:135], v[134:135], 1.0 op_sel_hi:[1,0]
	v_pk_add_f32 v[162:163], v[162:163], 1.0 op_sel_hi:[1,0]
	v_pk_add_f32 v[164:165], v[164:165], 1.0 op_sel_hi:[1,0]
	v_pk_add_f32 v[166:167], v[166:167], 1.0 op_sel_hi:[1,0]
	v_pk_add_f32 v[168:169], v[168:169], 1.0 op_sel_hi:[1,0]
	v_rcp_f32_e32 v128, v128
	v_rcp_f32_e32 v129, v129
	v_rcp_f32_e32 v130, v130
	v_rcp_f32_e32 v131, v131
	v_rcp_f32_e32 v132, v132
	v_rcp_f32_e32 v133, v133
	v_rcp_f32_e32 v134, v134
	v_rcp_f32_e32 v135, v135
	v_rcp_f32_e32 v162, v162
	v_rcp_f32_e32 v163, v163
	v_rcp_f32_e32 v164, v164
	v_rcp_f32_e32 v165, v165
	v_rcp_f32_e32 v166, v166
	v_rcp_f32_e32 v167, v167
	v_rcp_f32_e32 v168, v168
	v_rcp_f32_e32 v169, v169
	v_mov_b32_e32 v140, v251
	v_add_u32_e32 v174, 0x2c000, v251
	v_pk_mul_f32 v[124:125], v[124:125], v[128:129]
	v_pk_mul_f32 v[126:127], v[126:127], v[130:131]
	v_pk_mul_f32 v[116:117], v[116:117], v[132:133]
	v_pk_mul_f32 v[118:119], v[118:119], v[134:135]
	v_pk_mul_f32 v[108:109], v[108:109], v[162:163]
	v_pk_mul_f32 v[110:111], v[110:111], v[164:165]
	v_pk_mul_f32 v[100:101], v[100:101], v[166:167]
	v_pk_mul_f32 v[102:103], v[102:103], v[168:169]
	v_pk_mul_f32 v[124:125], v[124:125], v[120:121]
	v_pk_mul_f32 v[126:127], v[126:127], v[122:123]
	v_pk_mul_f32 v[116:117], v[116:117], v[112:113]
	v_pk_mul_f32 v[118:119], v[118:119], v[114:115]
	v_pk_mul_f32 v[108:109], v[108:109], v[104:105]
	v_pk_mul_f32 v[110:111], v[110:111], v[106:107]
	v_pk_mul_f32 v[100:101], v[100:101], v[96:97]
	v_pk_mul_f32 v[102:103], v[102:103], v[98:99]
	v_cvt_pk_bf16_f32 v136, v124, v125
	v_cvt_pk_bf16_f32 v137, v126, v127
	v_cvt_pk_bf16_f32 v138, v116, v117
	v_cvt_pk_bf16_f32 v139, v118, v119
	v_cvt_pk_bf16_f32 v170, v108, v109
	v_cvt_pk_bf16_f32 v171, v110, v111
	v_cvt_pk_bf16_f32 v172, v100, v101
	v_cvt_pk_bf16_f32 v173, v102, v103
	global_store_dwordx4 v140, v[136:139], s[28:29]
	global_store_dwordx4 v174, v[170:173], s[28:29]
	s_nop 1
	v_pk_mul_f32 v[92:93], v[92:93], v[236:237] op_sel_hi:[1,0]
	v_pk_mul_f32 v[94:95], v[94:95], v[236:237] op_sel_hi:[1,0]
	v_pk_mul_f32 v[84:85], v[84:85], v[236:237] op_sel_hi:[1,0]
	v_pk_mul_f32 v[86:87], v[86:87], v[236:237] op_sel_hi:[1,0]
	v_pk_mul_f32 v[76:77], v[76:77], v[238:239] op_sel_hi:[1,0]
	v_pk_mul_f32 v[78:79], v[78:79], v[238:239] op_sel_hi:[1,0]
	v_pk_mul_f32 v[68:69], v[68:69], v[238:239] op_sel_hi:[1,0]
	v_pk_mul_f32 v[70:71], v[70:71], v[238:239] op_sel_hi:[1,0]
	v_pk_mul_f32 v[128:129], v[92:93], v[248:249] op_sel_hi:[1,0]
	v_pk_mul_f32 v[130:131], v[94:95], v[248:249] op_sel_hi:[1,0]
	v_pk_mul_f32 v[132:133], v[84:85], v[248:249] op_sel_hi:[1,0]
	v_pk_mul_f32 v[134:135], v[86:87], v[248:249] op_sel_hi:[1,0]
	v_pk_mul_f32 v[162:163], v[76:77], v[248:249] op_sel_hi:[1,0]
	v_pk_mul_f32 v[164:165], v[78:79], v[248:249] op_sel_hi:[1,0]
	v_pk_mul_f32 v[166:167], v[68:69], v[248:249] op_sel_hi:[1,0]
	v_pk_mul_f32 v[168:169], v[70:71], v[248:249] op_sel_hi:[1,0]
	v_exp_f32_e32 v128, v128
	v_exp_f32_e32 v129, v129
	v_exp_f32_e32 v130, v130
	v_exp_f32_e32 v131, v131
	v_exp_f32_e32 v132, v132
	v_exp_f32_e32 v133, v133
	v_exp_f32_e32 v134, v134
	v_exp_f32_e32 v135, v135
	v_exp_f32_e32 v162, v162
	v_exp_f32_e32 v163, v163
	v_exp_f32_e32 v164, v164
	v_exp_f32_e32 v165, v165
	v_exp_f32_e32 v166, v166
	v_exp_f32_e32 v167, v167
	v_exp_f32_e32 v168, v168
	v_exp_f32_e32 v169, v169
	v_pk_mul_f32 v[88:89], v[88:89], v[236:237] op_sel_hi:[1,0]
	v_pk_mul_f32 v[90:91], v[90:91], v[236:237] op_sel_hi:[1,0]
	v_pk_mul_f32 v[80:81], v[80:81], v[236:237] op_sel_hi:[1,0]
	v_pk_mul_f32 v[82:83], v[82:83], v[236:237] op_sel_hi:[1,0]
	v_pk_mul_f32 v[72:73], v[72:73], v[238:239] op_sel_hi:[1,0]
	v_pk_mul_f32 v[74:75], v[74:75], v[238:239] op_sel_hi:[1,0]
; __device__ __forceinline__ unsigned cvt_pk_bf16(float lo, float hi) { unsigned r; asm volatile("v_cvt_pk_bf16_f32 %0, %1, %2" : "=v"(r) : "v"(lo), "v"(hi)); return r; }
; __device__ __forceinline__ float sigmoidf_(float x) { return fast_rcp(1.0f + fast_exp2(-1.4426950408889634f * x)); }
;     __device__ __forceinline__ void operator()(const f32x4 (&acc)[2][2][4][2], const Unit& u, int wr, int wc, int fr, int fq) const {
;     ...
;             for (int m = 0; m < 4; ++m) { const float sc = rs[ai][m]; f32x4 o[2];
; #pragma unroll
;                 for (int n = 0; n < 2; ++n) { const f32x4 g = acc[ai][0][m][n] * sc, up = acc[ai][1][m][n] * sc;
; #pragma unroll
;                     for (int e = 0; e < 4; ++e) o[n][e] = g[e] * sigmoidf_(g[e]) * up[e]; }
;                 u32x4 w; w.x = cvt_pk_bf16(o[0][0], o[0][1]); w.y = cvt_pk_bf16(o[0][2], o[0][3]); w.z = cvt_pk_bf16(o[1][0], o[1][1]); w.w = cvt_pk_bf16(o[1][2], o[1][3]);
;                 *(u32x4*)(O + (size_t)(row0 + ai * HALF + m * 16) * FF + col0) = w; }
	v_pk_mul_f32 v[64:65], v[64:65], v[238:239] op_sel_hi:[1,0]
	v_pk_mul_f32 v[66:67], v[66:67], v[238:239] op_sel_hi:[1,0]
	v_pk_add_f32 v[128:129], v[128:129], 1.0 op_sel_hi:[1,0]
	v_pk_add_f32 v[130:131], v[130:131], 1.0 op_sel_hi:[1,0]
	v_pk_add_f32 v[132:133], v[132:133], 1.0 op_sel_hi:[1,0]
	v_pk_add_f32 v[134:135], v[134:135], 1.0 op_sel_hi:[1,0]
	v_pk_add_f32 v[162:163], v[162:163], 1.0 op_sel_hi:[1,0]
	v_pk_add_f32 v[164:165], v[164:165], 1.0 op_sel_hi:[1,0]
	v_pk_add_f32 v[166:167], v[166:167], 1.0 op_sel_hi:[1,0]
	v_pk_add_f32 v[168:169], v[168:169], 1.0 op_sel_hi:[1,0]
	v_rcp_f32_e32 v128, v128
	v_rcp_f32_e32 v129, v129
	v_rcp_f32_e32 v130, v130
	v_rcp_f32_e32 v131, v131
	v_rcp_f32_e32 v132, v132
	v_rcp_f32_e32 v133, v133
	v_rcp_f32_e32 v134, v134
	v_rcp_f32_e32 v135, v135
	v_rcp_f32_e32 v162, v162
	v_rcp_f32_e32 v163, v163
	v_rcp_f32_e32 v164, v164
	v_rcp_f32_e32 v165, v165
	v_rcp_f32_e32 v166, v166
	v_rcp_f32_e32 v167, v167
	v_rcp_f32_e32 v168, v168
	v_rcp_f32_e32 v169, v169
	v_add_u32_e32 v140, 0x58000, v251
	v_add_u32_e32 v174, 0x84000, v251
	v_pk_mul_f32 v[92:93], v[92:93], v[128:129]
	v_pk_mul_f32 v[94:95], v[94:95], v[130:131]
	v_pk_mul_f32 v[84:85], v[84:85], v[132:133]
	v_pk_mul_f32 v[86:87], v[86:87], v[134:135]
	v_pk_mul_f32 v[76:77], v[76:77], v[162:163]
	v_pk_mul_f32 v[78:79], v[78:79], v[164:165]
	v_pk_mul_f32 v[68:69], v[68:69], v[166:167]
	v_pk_mul_f32 v[70:71], v[70:71], v[168:169]
	v_pk_mul_f32 v[92:93], v[92:93], v[88:89]
	v_pk_mul_f32 v[94:95], v[94:95], v[90:91]
	v_pk_mul_f32 v[84:85], v[84:85], v[80:81]
	v_pk_mul_f32 v[86:87], v[86:87], v[82:83]
	v_pk_mul_f32 v[76:77], v[76:77], v[72:73]
	v_pk_mul_f32 v[78:79], v[78:79], v[74:75]
	v_pk_mul_f32 v[68:69], v[68:69], v[64:65]
	v_pk_mul_f32 v[70:71], v[70:71], v[66:67]
	v_cvt_pk_bf16_f32 v136, v92, v93
	v_cvt_pk_bf16_f32 v137, v94, v95
	v_cvt_pk_bf16_f32 v138, v84, v85
	v_cvt_pk_bf16_f32 v139, v86, v87
	v_cvt_pk_bf16_f32 v170, v76, v77
	v_cvt_pk_bf16_f32 v171, v78, v79
	v_cvt_pk_bf16_f32 v172, v68, v69
	v_cvt_pk_bf16_f32 v173, v70, v71
	global_store_dwordx4 v140, v[136:139], s[28:29]
	global_store_dwordx4 v174, v[170:173], s[28:29]
	s_nop 1
	v_pk_mul_f32 v[60:61], v[60:61], v[240:241] op_sel_hi:[1,0]
	v_pk_mul_f32 v[62:63], v[62:63], v[240:241] op_sel_hi:[1,0]
	v_pk_mul_f32 v[52:53], v[52:53], v[240:241] op_sel_hi:[1,0]
	v_pk_mul_f32 v[54:55], v[54:55], v[240:241] op_sel_hi:[1,0]
	v_pk_mul_f32 v[44:45], v[44:45], v[242:243] op_sel_hi:[1,0]
	v_pk_mul_f32 v[46:47], v[46:47], v[242:243] op_sel_hi:[1,0]
	v_pk_mul_f32 v[36:37], v[36:37], v[242:243] op_sel_hi:[1,0]
	v_pk_mul_f32 v[38:39], v[38:39], v[242:243] op_sel_hi:[1,0]
	v_pk_mul_f32 v[128:129], v[60:61], v[248:249] op_sel_hi:[1,0]
	v_pk_mul_f32 v[130:131], v[62:63], v[248:249] op_sel_hi:[1,0]
	v_pk_mul_f32 v[132:133], v[52:53], v[248:249] op_sel_hi:[1,0]
	v_pk_mul_f32 v[134:135], v[54:55], v[248:249] op_sel_hi:[1,0]
	v_pk_mul_f32 v[162:163], v[44:45], v[248:249] op_sel_hi:[1,0]
	v_pk_mul_f32 v[164:165], v[46:47], v[248:249] op_sel_hi:[1,0]
	v_pk_mul_f32 v[166:167], v[36:37], v[248:249] op_sel_hi:[1,0]
	v_pk_mul_f32 v[168:169], v[38:39], v[248:249] op_sel_hi:[1,0]
	v_exp_f32_e32 v128, v128
	v_exp_f32_e32 v129, v129
	v_exp_f32_e32 v130, v130
	v_exp_f32_e32 v131, v131
	v_exp_f32_e32 v132, v132
	v_exp_f32_e32 v133, v133
	v_exp_f32_e32 v134, v134
	v_exp_f32_e32 v135, v135
	v_exp_f32_e32 v162, v162
	v_exp_f32_e32 v163, v163
	v_exp_f32_e32 v164, v164
	v_exp_f32_e32 v165, v165
	v_exp_f32_e32 v166, v166
	v_exp_f32_e32 v167, v167
	v_exp_f32_e32 v168, v168
	v_exp_f32_e32 v169, v169
	v_pk_mul_f32 v[56:57], v[56:57], v[240:241] op_sel_hi:[1,0]
	v_pk_mul_f32 v[58:59], v[58:59], v[240:241] op_sel_hi:[1,0]
	v_pk_mul_f32 v[48:49], v[48:49], v[240:241] op_sel_hi:[1,0]
	v_pk_mul_f32 v[50:51], v[50:51], v[240:241] op_sel_hi:[1,0]
	v_pk_mul_f32 v[40:41], v[40:41], v[242:243] op_sel_hi:[1,0]
	v_pk_mul_f32 v[42:43], v[42:43], v[242:243] op_sel_hi:[1,0]
	v_pk_mul_f32 v[32:33], v[32:33], v[242:243] op_sel_hi:[1,0]
	v_pk_mul_f32 v[34:35], v[34:35], v[242:243] op_sel_hi:[1,0]
	v_pk_add_f32 v[128:129], v[128:129], 1.0 op_sel_hi:[1,0]
	v_pk_add_f32 v[130:131], v[130:131], 1.0 op_sel_hi:[1,0]
	v_pk_add_f32 v[132:133], v[132:133], 1.0 op_sel_hi:[1,0]
	v_pk_add_f32 v[134:135], v[134:135], 1.0 op_sel_hi:[1,0]
	v_pk_add_f32 v[162:163], v[162:163], 1.0 op_sel_hi:[1,0]
	v_pk_add_f32 v[164:165], v[164:165], 1.0 op_sel_hi:[1,0]
	v_pk_add_f32 v[166:167], v[166:167], 1.0 op_sel_hi:[1,0]
	v_pk_add_f32 v[168:169], v[168:169], 1.0 op_sel_hi:[1,0]
	v_rcp_f32_e32 v128, v128
	v_rcp_f32_e32 v129, v129
	v_rcp_f32_e32 v130, v130
	v_rcp_f32_e32 v131, v131
	v_rcp_f32_e32 v132, v132
	v_rcp_f32_e32 v133, v133
	v_rcp_f32_e32 v134, v134
	v_rcp_f32_e32 v135, v135
	v_rcp_f32_e32 v162, v162
	v_rcp_f32_e32 v163, v163
	v_rcp_f32_e32 v164, v164
	v_rcp_f32_e32 v165, v165
	v_rcp_f32_e32 v166, v166
	v_rcp_f32_e32 v167, v167
	v_rcp_f32_e32 v168, v168
	v_rcp_f32_e32 v169, v169
	v_add_u32_e32 v140, 0x160000, v251
	v_add_u32_e32 v174, 0x18c000, v251
	v_pk_mul_f32 v[60:61], v[60:61], v[128:129]
; __device__ __forceinline__ unsigned cvt_pk_bf16(float lo, float hi) { unsigned r; asm volatile("v_cvt_pk_bf16_f32 %0, %1, %2" : "=v"(r) : "v"(lo), "v"(hi)); return r; }
; __device__ __forceinline__ float sigmoidf_(float x) { return fast_rcp(1.0f + fast_exp2(-1.4426950408889634f * x)); }
;     __device__ __forceinline__ void operator()(const f32x4 (&acc)[2][2][4][2], const Unit& u, int wr, int wc, int fr, int fq) const {
;     ...
;             for (int m = 0; m < 4; ++m) { const float sc = rs[ai][m]; f32x4 o[2];
; #pragma unroll
;                 for (int n = 0; n < 2; ++n) { const f32x4 g = acc[ai][0][m][n] * sc, up = acc[ai][1][m][n] * sc;
; #pragma unroll
;                     for (int e = 0; e < 4; ++e) o[n][e] = g[e] * sigmoidf_(g[e]) * up[e]; }
;                 u32x4 w; w.x = cvt_pk_bf16(o[0][0], o[0][1]); w.y = cvt_pk_bf16(o[0][2], o[0][3]); w.z = cvt_pk_bf16(o[1][0], o[1][1]); w.w = cvt_pk_bf16(o[1][2], o[1][3]);
;                 *(u32x4*)(O + (size_t)(row0 + ai * HALF + m * 16) * FF + col0) = w; }
	v_pk_mul_f32 v[62:63], v[62:63], v[130:131]
	v_pk_mul_f32 v[52:53], v[52:53], v[132:133]
	v_pk_mul_f32 v[54:55], v[54:55], v[134:135]
	v_pk_mul_f32 v[44:45], v[44:45], v[162:163]
	v_pk_mul_f32 v[46:47], v[46:47], v[164:165]
	v_pk_mul_f32 v[36:37], v[36:37], v[166:167]
	v_pk_mul_f32 v[38:39], v[38:39], v[168:169]
	v_pk_mul_f32 v[60:61], v[60:61], v[56:57]
	v_pk_mul_f32 v[62:63], v[62:63], v[58:59]
	v_pk_mul_f32 v[52:53], v[52:53], v[48:49]
	v_pk_mul_f32 v[54:55], v[54:55], v[50:51]
	v_pk_mul_f32 v[44:45], v[44:45], v[40:41]
	v_pk_mul_f32 v[46:47], v[46:47], v[42:43]
	v_pk_mul_f32 v[36:37], v[36:37], v[32:33]
	v_pk_mul_f32 v[38:39], v[38:39], v[34:35]
	v_cvt_pk_bf16_f32 v136, v60, v61
	v_cvt_pk_bf16_f32 v137, v62, v63
	v_cvt_pk_bf16_f32 v138, v52, v53
	v_cvt_pk_bf16_f32 v139, v54, v55
	v_cvt_pk_bf16_f32 v170, v44, v45
	v_cvt_pk_bf16_f32 v171, v46, v47
	v_cvt_pk_bf16_f32 v172, v36, v37
	v_cvt_pk_bf16_f32 v173, v38, v39
	global_store_dwordx4 v140, v[136:139], s[28:29]
	global_store_dwordx4 v174, v[170:173], s[28:29]
	s_nop 1
	v_pk_mul_f32 v[28:29], v[28:29], v[244:245] op_sel_hi:[1,0]
	v_pk_mul_f32 v[30:31], v[30:31], v[244:245] op_sel_hi:[1,0]
	v_pk_mul_f32 v[20:21], v[20:21], v[244:245] op_sel_hi:[1,0]
	v_pk_mul_f32 v[22:23], v[22:23], v[244:245] op_sel_hi:[1,0]
	v_pk_mul_f32 v[12:13], v[12:13], v[246:247] op_sel_hi:[1,0]
	v_pk_mul_f32 v[14:15], v[14:15], v[246:247] op_sel_hi:[1,0]
	v_pk_mul_f32 v[4:5], v[4:5], v[246:247] op_sel_hi:[1,0]
	v_pk_mul_f32 v[6:7], v[6:7], v[246:247] op_sel_hi:[1,0]
	v_pk_mul_f32 v[128:129], v[28:29], v[248:249] op_sel_hi:[1,0]
	v_pk_mul_f32 v[130:131], v[30:31], v[248:249] op_sel_hi:[1,0]
	v_pk_mul_f32 v[132:133], v[20:21], v[248:249] op_sel_hi:[1,0]
	v_pk_mul_f32 v[134:135], v[22:23], v[248:249] op_sel_hi:[1,0]
	v_pk_mul_f32 v[162:163], v[12:13], v[248:249] op_sel_hi:[1,0]
	v_pk_mul_f32 v[164:165], v[14:15], v[248:249] op_sel_hi:[1,0]
	v_pk_mul_f32 v[166:167], v[4:5], v[248:249] op_sel_hi:[1,0]
	v_pk_mul_f32 v[168:169], v[6:7], v[248:249] op_sel_hi:[1,0]
	v_exp_f32_e32 v128, v128
	v_exp_f32_e32 v129, v129
	v_exp_f32_e32 v130, v130
	v_exp_f32_e32 v131, v131
	v_exp_f32_e32 v132, v132
	v_exp_f32_e32 v133, v133
	v_exp_f32_e32 v134, v134
	v_exp_f32_e32 v135, v135
	v_exp_f32_e32 v162, v162
	v_exp_f32_e32 v163, v163
	v_exp_f32_e32 v164, v164
	v_exp_f32_e32 v165, v165
	v_exp_f32_e32 v166, v166
	v_exp_f32_e32 v167, v167
	v_exp_f32_e32 v168, v168
	v_exp_f32_e32 v169, v169
	v_pk_mul_f32 v[24:25], v[24:25], v[244:245] op_sel_hi:[1,0]
	v_pk_mul_f32 v[26:27], v[26:27], v[244:245] op_sel_hi:[1,0]
	v_pk_mul_f32 v[16:17], v[16:17], v[244:245] op_sel_hi:[1,0]
	v_pk_mul_f32 v[18:19], v[18:19], v[244:245] op_sel_hi:[1,0]
	v_pk_mul_f32 v[8:9], v[8:9], v[246:247] op_sel_hi:[1,0]
	v_pk_mul_f32 v[10:11], v[10:11], v[246:247] op_sel_hi:[1,0]
	v_pk_mul_f32 v[0:1], v[0:1], v[246:247] op_sel_hi:[1,0]
	v_pk_mul_f32 v[2:3], v[2:3], v[246:247] op_sel_hi:[1,0]
	v_pk_add_f32 v[128:129], v[128:129], 1.0 op_sel_hi:[1,0]
	v_pk_add_f32 v[130:131], v[130:131], 1.0 op_sel_hi:[1,0]
	v_pk_add_f32 v[132:133], v[132:133], 1.0 op_sel_hi:[1,0]
	v_pk_add_f32 v[134:135], v[134:135], 1.0 op_sel_hi:[1,0]
	v_pk_add_f32 v[162:163], v[162:163], 1.0 op_sel_hi:[1,0]
	v_pk_add_f32 v[164:165], v[164:165], 1.0 op_sel_hi:[1,0]
	v_pk_add_f32 v[166:167], v[166:167], 1.0 op_sel_hi:[1,0]
	v_pk_add_f32 v[168:169], v[168:169], 1.0 op_sel_hi:[1,0]
	v_rcp_f32_e32 v128, v128
	v_rcp_f32_e32 v129, v129
	v_rcp_f32_e32 v130, v130
	v_rcp_f32_e32 v131, v131
	v_rcp_f32_e32 v132, v132
	v_rcp_f32_e32 v133, v133
	v_rcp_f32_e32 v134, v134
	v_rcp_f32_e32 v135, v135
	v_rcp_f32_e32 v162, v162
	v_rcp_f32_e32 v163, v163
	v_rcp_f32_e32 v164, v164
	v_rcp_f32_e32 v165, v165
	v_rcp_f32_e32 v166, v166
	v_rcp_f32_e32 v167, v167
	v_rcp_f32_e32 v168, v168
	v_rcp_f32_e32 v169, v169
	v_add_u32_e32 v140, 0x1b8000, v251
	v_add_u32_e32 v174, 0x1e4000, v251
	v_pk_mul_f32 v[28:29], v[28:29], v[128:129]
	v_pk_mul_f32 v[30:31], v[30:31], v[130:131]
	v_pk_mul_f32 v[20:21], v[20:21], v[132:133]
	v_pk_mul_f32 v[22:23], v[22:23], v[134:135]
	v_pk_mul_f32 v[12:13], v[12:13], v[162:163]
	v_pk_mul_f32 v[14:15], v[14:15], v[164:165]
	v_pk_mul_f32 v[4:5], v[4:5], v[166:167]
	v_pk_mul_f32 v[6:7], v[6:7], v[168:169]
	v_pk_mul_f32 v[28:29], v[28:29], v[24:25]
	v_pk_mul_f32 v[30:31], v[30:31], v[26:27]
	v_pk_mul_f32 v[20:21], v[20:21], v[16:17]
	v_pk_mul_f32 v[22:23], v[22:23], v[18:19]
	v_pk_mul_f32 v[12:13], v[12:13], v[8:9]
	v_pk_mul_f32 v[14:15], v[14:15], v[10:11]
	v_pk_mul_f32 v[4:5], v[4:5], v[0:1]
	v_pk_mul_f32 v[6:7], v[6:7], v[2:3]
	v_cvt_pk_bf16_f32 v136, v28, v29
	v_cvt_pk_bf16_f32 v137, v30, v31
	v_cvt_pk_bf16_f32 v138, v20, v21
	v_cvt_pk_bf16_f32 v139, v22, v23
	v_cvt_pk_bf16_f32 v170, v12, v13
	v_cvt_pk_bf16_f32 v171, v14, v15
	v_cvt_pk_bf16_f32 v172, v4, v5
	v_cvt_pk_bf16_f32 v173, v6, v7
	global_store_dwordx4 v140, v[136:139], s[28:29]
	global_store_dwordx4 v174, v[170:173], s[28:29]
	s_andn2_b64 vcc, exec, s[2:3]
	s_mov_b64 s[2:3], -1
	s_cbranch_vccnz .LBB0_257
	s_andn2_b64 vcc, exec, s[26:27]
	s_cbranch_vccnz .LBB0_256
	s_barrier
	s_branch .LBB0_256

; __device__ __forceinline__ void load_rstd(const float* part, int row0, int fq, float (&rs)[2][4]) {
; #pragma unroll
;     for (int ai = 0; ai < 2; ++ai)
; #pragma unroll
;         for (int m = 0; m < 4; ++m) { const float* p = part + (size_t)(row0 + ai * HALF + m * 16) * NPART + fq * 8;
;             const f32x4 a = *(const f32x4*)p, b = *(const f32x4*)(p + 4); float s = ((a[0] + a[1]) + (a[2] + a[3])) + ((b[0] + b[1]) + (b[2] + b[3]));
;             s += __shfl_xor(s, 16); s += __shfl_xor(s, 32); rs[ai][m] = rsqrtf(s * (1.0f / D) + RMS_EPS); }
;     __device__ __forceinline__ void operator()(const f32x4 (&acc)[2][2][4][2], const Unit& u, int wr, int wc, int fr, int fq) const {
;         const int row0 = u.pm * BM + wr * 64 + fr, col0 = u.pn * HALF + wc * 32 + 8 * fq;
;         float rs[2][4]; load_rstd(part, row0, fq, rs);
; #pragma unroll
;         for (int ai = 0; ai < 2; ++ai)
; #pragma unroll
;             for (int m = 0; m < 4; ++m) { const float sc = rs[ai][m]; f32x4 o[2];
; #pragma unroll
;                 for (int n = 0; n < 2; ++n) { const f32x4 g = acc[ai][0][m][n] * sc, up = acc[ai][1][m][n] * sc;
.LBB0_1151:
	v_lshl_add_u32 v237, s11, 8, v181
	s_mov_b64 vcc, 0x1000
	s_mov_b64 s[100:101], 0x4000
	v_ashrrev_i32_e32 v179, 31, v237
	v_mov_b32_e32 v178, v237
	v_lshlrev_b64 v[178:179], 7, v[178:179]
	v_lshl_add_u64 v[178:179], v[152:153], 0, v[178:179]
	v_lshl_add_u64 v[222:223], v[178:179], 0, vcc
	v_lshl_add_u64 v[224:225], v[178:179], 0, s[100:101]
	v_lshl_add_u64 v[226:227], v[224:225], 0, vcc
	global_load_dwordx4 v[128:131], v[178:179], off
	global_load_dwordx4 v[132:135], v[178:179], off offset:16
	global_load_dwordx4 v[136:139], v[178:179], off offset:2048
	global_load_dwordx4 v[140:143], v[178:179], off offset:2064
	global_load_dwordx4 v[162:165], v[222:223], off
	global_load_dwordx4 v[166:169], v[222:223], off offset:16
	global_load_dwordx4 v[170:173], v[222:223], off offset:2048
	global_load_dwordx4 v[174:177], v[222:223], off offset:2064
	global_load_dwordx4 v[188:191], v[224:225], off
	global_load_dwordx4 v[192:195], v[224:225], off offset:16
	global_load_dwordx4 v[196:199], v[224:225], off offset:2048
	global_load_dwordx4 v[200:203], v[224:225], off offset:2064
	global_load_dwordx4 v[204:207], v[226:227], off
	global_load_dwordx4 v[208:211], v[226:227], off offset:16
	global_load_dwordx4 v[212:215], v[226:227], off offset:2048
	global_load_dwordx4 v[216:219], v[226:227], off offset:2064
	v_mov_b32_e32 v236, 0xbfb8aa3b
	v_mov_b32_e32 v238, 0x358637bd
	v_lshl_or_b32 v239, s73, 7, v183
	v_lshlrev_b32_e32 v239, 1, v239
	v_mul_u32_u24_e32 v237, 0x2c00, v237
	v_add_u32_e32 v239, v239, v237
	s_waitcnt vmcnt(0)
	v_add_f32_e32 v128, v128, v129
	v_add_f32_e32 v130, v130, v131
	v_add_f32_e32 v132, v132, v133
	v_add_f32_e32 v134, v134, v135
	v_add_f32_e32 v136, v136, v137
	v_add_f32_e32 v138, v138, v139
	v_add_f32_e32 v140, v140, v141
	v_add_f32_e32 v142, v142, v143
	v_add_f32_e32 v162, v162, v163
	v_add_f32_e32 v164, v164, v165
	v_add_f32_e32 v166, v166, v167
	v_add_f32_e32 v168, v168, v169
	v_add_f32_e32 v170, v170, v171
	v_add_f32_e32 v172, v172, v173
	v_add_f32_e32 v174, v174, v175
	v_add_f32_e32 v176, v176, v177
	v_add_f32_e32 v188, v188, v189
	v_add_f32_e32 v190, v190, v191
	v_add_f32_e32 v192, v192, v193
	v_add_f32_e32 v194, v194, v195
	v_add_f32_e32 v196, v196, v197
	v_add_f32_e32 v198, v198, v199
	v_add_f32_e32 v200, v200, v201
	v_add_f32_e32 v202, v202, v203
	v_add_f32_e32 v204, v204, v205
	v_add_f32_e32 v206, v206, v207
	v_add_f32_e32 v208, v208, v209
	v_add_f32_e32 v210, v210, v211
	v_add_f32_e32 v212, v212, v213
	v_add_f32_e32 v214, v214, v215
	v_add_f32_e32 v216, v216, v217
	v_add_f32_e32 v218, v218, v219
	v_add_f32_e32 v128, v128, v130
	v_add_f32_e32 v132, v132, v134
	v_add_f32_e32 v136, v136, v138
	v_add_f32_e32 v140, v140, v142
	v_add_f32_e32 v162, v162, v164
	v_add_f32_e32 v166, v166, v168
	v_add_f32_e32 v170, v170, v172
	v_add_f32_e32 v174, v174, v176
	v_add_f32_e32 v188, v188, v190
	v_add_f32_e32 v192, v192, v194
	v_add_f32_e32 v196, v196, v198
	v_add_f32_e32 v200, v200, v202
	v_add_f32_e32 v204, v204, v206
	v_add_f32_e32 v208, v208, v210
	v_add_f32_e32 v212, v212, v214
	v_add_f32_e32 v216, v216, v218
	v_add_f32_e32 v128, v128, v132
	v_add_f32_e32 v136, v136, v140
	v_add_f32_e32 v162, v162, v166
	v_add_f32_e32 v170, v170, v174
	v_add_f32_e32 v188, v188, v192
	v_add_f32_e32 v196, v196, v200
	v_add_f32_e32 v204, v204, v208
	v_add_f32_e32 v212, v212, v216
	v_mov_b32_e32 v179, v128
	v_mov_b32_e32 v223, v136
	v_mov_b32_e32 v225, v162
	v_mov_b32_e32 v227, v170
	v_mov_b32_e32 v229, v188
	v_mov_b32_e32 v231, v196
	v_mov_b32_e32 v233, v204
	v_mov_b32_e32 v235, v212
	s_nop 1
	v_permlane16_swap_b32_e32 v128, v179
	v_permlane16_swap_b32_e32 v136, v223
	v_permlane16_swap_b32_e32 v162, v225
	v_permlane16_swap_b32_e32 v170, v227
	v_permlane16_swap_b32_e32 v188, v229
	v_permlane16_swap_b32_e32 v196, v231
	v_permlane16_swap_b32_e32 v204, v233
	v_permlane16_swap_b32_e32 v212, v235
	v_add_f32_e32 v128, v128, v179
	v_add_f32_e32 v136, v136, v223
	v_add_f32_e32 v162, v162, v225
	v_add_f32_e32 v170, v170, v227
	v_add_f32_e32 v188, v188, v229
	v_add_f32_e32 v196, v196, v231
	v_add_f32_e32 v204, v204, v233
	v_add_f32_e32 v212, v212, v235
	v_mov_b32_e32 v179, v128
	v_mov_b32_e32 v223, v136
	v_mov_b32_e32 v225, v162
	v_mov_b32_e32 v227, v170
	v_mov_b32_e32 v229, v188
	v_mov_b32_e32 v231, v196
	v_mov_b32_e32 v233, v204
	v_mov_b32_e32 v235, v212
	s_nop 1
	v_permlane32_swap_b32_e32 v128, v179
	v_permlane32_swap_b32_e32 v136, v223
	v_permlane32_swap_b32_e32 v162, v225
	v_permlane32_swap_b32_e32 v170, v227
	v_permlane32_swap_b32_e32 v188, v229
	v_permlane32_swap_b32_e32 v196, v231
	v_permlane32_swap_b32_e32 v204, v233
	v_permlane32_swap_b32_e32 v212, v235
	v_add_f32_e32 v128, v128, v179
	v_add_f32_e32 v136, v136, v223
	v_add_f32_e32 v162, v162, v225
	v_add_f32_e32 v170, v170, v227
	v_add_f32_e32 v188, v188, v229
	v_add_f32_e32 v196, v196, v231
	v_add_f32_e32 v204, v204, v233
	v_add_f32_e32 v212, v212, v235
	v_fmamk_f32 v178, v128, 0x3a000000, v238
	v_fmamk_f32 v222, v136, 0x3a000000, v238
	v_fmamk_f32 v224, v162, 0x3a000000, v238
	v_fmamk_f32 v226, v170, 0x3a000000, v238
	v_fmamk_f32 v228, v188, 0x3a000000, v238
	v_fmamk_f32 v230, v196, 0x3a000000, v238
	v_fmamk_f32 v232, v204, 0x3a000000, v238
	v_fmamk_f32 v234, v212, 0x3a000000, v238
	v_rsq_f32_e32 v178, v178
	v_rsq_f32_e32 v222, v222
	v_rsq_f32_e32 v224, v224
	v_rsq_f32_e32 v226, v226
	v_rsq_f32_e32 v228, v228
	v_rsq_f32_e32 v230, v230
	v_rsq_f32_e32 v232, v232
	v_rsq_f32_e32 v234, v234
	v_pk_mul_f32 v[124:125], v[124:125], v[178:179] op_sel_hi:[1,0]
	v_pk_mul_f32 v[126:127], v[126:127], v[178:179] op_sel_hi:[1,0]
	v_pk_mul_f32 v[116:117], v[116:117], v[178:179] op_sel_hi:[1,0]
; __device__ __forceinline__ unsigned cvt_pk_bf16(float lo, float hi) { unsigned r; asm volatile("v_cvt_pk_bf16_f32 %0, %1, %2" : "=v"(r) : "v"(lo), "v"(hi)); return r; }
; __device__ __forceinline__ float sigmoidf_(float x) { return fast_rcp(1.0f + fast_exp2(-1.4426950408889634f * x)); }
;     __device__ __forceinline__ void operator()(const f32x4 (&acc)[2][2][4][2], const Unit& u, int wr, int wc, int fr, int fq) const {
;     ...
;             for (int m = 0; m < 4; ++m) { const float sc = rs[ai][m]; f32x4 o[2];
; #pragma unroll
;                 for (int n = 0; n < 2; ++n) { const f32x4 g = acc[ai][0][m][n] * sc, up = acc[ai][1][m][n] * sc;
; #pragma unroll
;                     for (int e = 0; e < 4; ++e) o[n][e] = g[e] * sigmoidf_(g[e]) * up[e]; }
;                 u32x4 w; w.x = cvt_pk_bf16(o[0][0], o[0][1]); w.y = cvt_pk_bf16(o[0][2], o[0][3]); w.z = cvt_pk_bf16(o[1][0], o[1][1]); w.w = cvt_pk_bf16(o[1][2], o[1][3]);
;                 *(u32x4*)(O + (size_t)(row0 + ai * HALF + m * 16) * FF + col0) = w; }
	v_pk_mul_f32 v[118:119], v[118:119], v[178:179] op_sel_hi:[1,0]
	v_pk_mul_f32 v[108:109], v[108:109], v[222:223] op_sel_hi:[1,0]
	v_pk_mul_f32 v[110:111], v[110:111], v[222:223] op_sel_hi:[1,0]
	v_pk_mul_f32 v[100:101], v[100:101], v[222:223] op_sel_hi:[1,0]
	v_pk_mul_f32 v[102:103], v[102:103], v[222:223] op_sel_hi:[1,0]
	v_pk_mul_f32 v[128:129], v[124:125], v[236:237] op_sel_hi:[1,0]
	v_pk_mul_f32 v[130:131], v[126:127], v[236:237] op_sel_hi:[1,0]
	v_pk_mul_f32 v[132:133], v[116:117], v[236:237] op_sel_hi:[1,0]
	v_pk_mul_f32 v[134:135], v[118:119], v[236:237] op_sel_hi:[1,0]
	v_pk_mul_f32 v[162:163], v[108:109], v[236:237] op_sel_hi:[1,0]
	v_pk_mul_f32 v[164:165], v[110:111], v[236:237] op_sel_hi:[1,0]
	v_pk_mul_f32 v[166:167], v[100:101], v[236:237] op_sel_hi:[1,0]
	v_pk_mul_f32 v[168:169], v[102:103], v[236:237] op_sel_hi:[1,0]
	v_exp_f32_e32 v128, v128
	v_exp_f32_e32 v129, v129
	v_exp_f32_e32 v130, v130
	v_exp_f32_e32 v131, v131
	v_exp_f32_e32 v132, v132
	v_exp_f32_e32 v133, v133
	v_exp_f32_e32 v134, v134
	v_exp_f32_e32 v135, v135
	v_exp_f32_e32 v162, v162
	v_exp_f32_e32 v163, v163
	v_exp_f32_e32 v164, v164
	v_exp_f32_e32 v165, v165
	v_exp_f32_e32 v166, v166
	v_exp_f32_e32 v167, v167
	v_exp_f32_e32 v168, v168
	v_exp_f32_e32 v169, v169
	v_pk_mul_f32 v[120:121], v[120:121], v[178:179] op_sel_hi:[1,0]
	v_pk_mul_f32 v[122:123], v[122:123], v[178:179] op_sel_hi:[1,0]
	v_pk_mul_f32 v[112:113], v[112:113], v[178:179] op_sel_hi:[1,0]
	v_pk_mul_f32 v[114:115], v[114:115], v[178:179] op_sel_hi:[1,0]
	v_pk_mul_f32 v[104:105], v[104:105], v[222:223] op_sel_hi:[1,0]
	v_pk_mul_f32 v[106:107], v[106:107], v[222:223] op_sel_hi:[1,0]
	v_pk_mul_f32 v[96:97], v[96:97], v[222:223] op_sel_hi:[1,0]
	v_pk_mul_f32 v[98:99], v[98:99], v[222:223] op_sel_hi:[1,0]
	v_pk_add_f32 v[128:129], v[128:129], 1.0 op_sel_hi:[1,0]
	v_pk_add_f32 v[130:131], v[130:131], 1.0 op_sel_hi:[1,0]
	v_pk_add_f32 v[132:133], v[132:133], 1.0 op_sel_hi:[1,0]
	v_pk_add_f32 v[134:135], v[134:135], 1.0 op_sel_hi:[1,0]
	v_pk_add_f32 v[162:163], v[162:163], 1.0 op_sel_hi:[1,0]
	v_pk_add_f32 v[164:165], v[164:165], 1.0 op_sel_hi:[1,0]
	v_pk_add_f32 v[166:167], v[166:167], 1.0 op_sel_hi:[1,0]
	v_pk_add_f32 v[168:169], v[168:169], 1.0 op_sel_hi:[1,0]
	v_rcp_f32_e32 v128, v128
	v_rcp_f32_e32 v129, v129
	v_rcp_f32_e32 v130, v130
	v_rcp_f32_e32 v131, v131
	v_rcp_f32_e32 v132, v132
	v_rcp_f32_e32 v133, v133
	v_rcp_f32_e32 v134, v134
	v_rcp_f32_e32 v135, v135
	v_rcp_f32_e32 v162, v162
	v_rcp_f32_e32 v163, v163
	v_rcp_f32_e32 v164, v164
	v_rcp_f32_e32 v165, v165
	v_rcp_f32_e32 v166, v166
	v_rcp_f32_e32 v167, v167
	v_rcp_f32_e32 v168, v168
	v_rcp_f32_e32 v169, v169
	v_mov_b32_e32 v140, v239
	v_add_u32_e32 v174, 0x2c000, v239
	v_pk_mul_f32 v[124:125], v[124:125], v[128:129]
	v_pk_mul_f32 v[126:127], v[126:127], v[130:131]
	v_pk_mul_f32 v[116:117], v[116:117], v[132:133]
	v_pk_mul_f32 v[118:119], v[118:119], v[134:135]
	v_pk_mul_f32 v[108:109], v[108:109], v[162:163]
	v_pk_mul_f32 v[110:111], v[110:111], v[164:165]
	v_pk_mul_f32 v[100:101], v[100:101], v[166:167]
	v_pk_mul_f32 v[102:103], v[102:103], v[168:169]
	v_pk_mul_f32 v[124:125], v[124:125], v[120:121]
	v_pk_mul_f32 v[126:127], v[126:127], v[122:123]
	v_pk_mul_f32 v[116:117], v[116:117], v[112:113]
	v_pk_mul_f32 v[118:119], v[118:119], v[114:115]
	v_pk_mul_f32 v[108:109], v[108:109], v[104:105]
	v_pk_mul_f32 v[110:111], v[110:111], v[106:107]
	v_pk_mul_f32 v[100:101], v[100:101], v[96:97]
	v_pk_mul_f32 v[102:103], v[102:103], v[98:99]
	v_cvt_pk_bf16_f32 v136, v124, v125
	v_cvt_pk_bf16_f32 v137, v126, v127
	v_cvt_pk_bf16_f32 v138, v116, v117
	v_cvt_pk_bf16_f32 v139, v118, v119
	v_cvt_pk_bf16_f32 v170, v108, v109
	v_cvt_pk_bf16_f32 v171, v110, v111
	v_cvt_pk_bf16_f32 v172, v100, v101
	v_cvt_pk_bf16_f32 v173, v102, v103
	global_store_dwordx4 v140, v[136:139], s[28:29]
	global_store_dwordx4 v174, v[170:173], s[28:29]
	s_nop 1
	v_pk_mul_f32 v[92:93], v[92:93], v[224:225] op_sel_hi:[1,0]
	v_pk_mul_f32 v[94:95], v[94:95], v[224:225] op_sel_hi:[1,0]
	v_pk_mul_f32 v[84:85], v[84:85], v[224:225] op_sel_hi:[1,0]
	v_pk_mul_f32 v[86:87], v[86:87], v[224:225] op_sel_hi:[1,0]
	v_pk_mul_f32 v[76:77], v[76:77], v[226:227] op_sel_hi:[1,0]
	v_pk_mul_f32 v[78:79], v[78:79], v[226:227] op_sel_hi:[1,0]
	v_pk_mul_f32 v[68:69], v[68:69], v[226:227] op_sel_hi:[1,0]
	v_pk_mul_f32 v[70:71], v[70:71], v[226:227] op_sel_hi:[1,0]
	v_pk_mul_f32 v[128:129], v[92:93], v[236:237] op_sel_hi:[1,0]
	v_pk_mul_f32 v[130:131], v[94:95], v[236:237] op_sel_hi:[1,0]
	v_pk_mul_f32 v[132:133], v[84:85], v[236:237] op_sel_hi:[1,0]
	v_pk_mul_f32 v[134:135], v[86:87], v[236:237] op_sel_hi:[1,0]
	v_pk_mul_f32 v[162:163], v[76:77], v[236:237] op_sel_hi:[1,0]
	v_pk_mul_f32 v[164:165], v[78:79], v[236:237] op_sel_hi:[1,0]
	v_pk_mul_f32 v[166:167], v[68:69], v[236:237] op_sel_hi:[1,0]
	v_pk_mul_f32 v[168:169], v[70:71], v[236:237] op_sel_hi:[1,0]
	v_exp_f32_e32 v128, v128
	v_exp_f32_e32 v129, v129
	v_exp_f32_e32 v130, v130
	v_exp_f32_e32 v131, v131
	v_exp_f32_e32 v132, v132
	v_exp_f32_e32 v133, v133
	v_exp_f32_e32 v134, v134
	v_exp_f32_e32 v135, v135
	v_exp_f32_e32 v162, v162
	v_exp_f32_e32 v163, v163
	v_exp_f32_e32 v164, v164
	v_exp_f32_e32 v165, v165
	v_exp_f32_e32 v166, v166
	v_exp_f32_e32 v167, v167
	v_exp_f32_e32 v168, v168
	v_exp_f32_e32 v169, v169
	v_pk_mul_f32 v[88:89], v[88:89], v[224:225] op_sel_hi:[1,0]
	v_pk_mul_f32 v[90:91], v[90:91], v[224:225] op_sel_hi:[1,0]
	v_pk_mul_f32 v[80:81], v[80:81], v[224:225] op_sel_hi:[1,0]
	v_pk_mul_f32 v[82:83], v[82:83], v[224:225] op_sel_hi:[1,0]
	v_pk_mul_f32 v[72:73], v[72:73], v[226:227] op_sel_hi:[1,0]
	v_pk_mul_f32 v[74:75], v[74:75], v[226:227] op_sel_hi:[1,0]
; __device__ __forceinline__ unsigned cvt_pk_bf16(float lo, float hi) { unsigned r; asm volatile("v_cvt_pk_bf16_f32 %0, %1, %2" : "=v"(r) : "v"(lo), "v"(hi)); return r; }
; __device__ __forceinline__ float sigmoidf_(float x) { return fast_rcp(1.0f + fast_exp2(-1.4426950408889634f * x)); }
;     __device__ __forceinline__ void operator()(const f32x4 (&acc)[2][2][4][2], const Unit& u, int wr, int wc, int fr, int fq) const {
;     ...
;             for (int m = 0; m < 4; ++m) { const float sc = rs[ai][m]; f32x4 o[2];
; #pragma unroll
;                 for (int n = 0; n < 2; ++n) { const f32x4 g = acc[ai][0][m][n] * sc, up = acc[ai][1][m][n] * sc;
; #pragma unroll
;                     for (int e = 0; e < 4; ++e) o[n][e] = g[e] * sigmoidf_(g[e]) * up[e]; }
;                 u32x4 w; w.x = cvt_pk_bf16(o[0][0], o[0][1]); w.y = cvt_pk_bf16(o[0][2], o[0][3]); w.z = cvt_pk_bf16(o[1][0], o[1][1]); w.w = cvt_pk_bf16(o[1][2], o[1][3]);
;                 *(u32x4*)(O + (size_t)(row0 + ai * HALF + m * 16) * FF + col0) = w; }
	v_pk_mul_f32 v[64:65], v[64:65], v[226:227] op_sel_hi:[1,0]
	v_pk_mul_f32 v[66:67], v[66:67], v[226:227] op_sel_hi:[1,0]
	v_pk_add_f32 v[128:129], v[128:129], 1.0 op_sel_hi:[1,0]
	v_pk_add_f32 v[130:131], v[130:131], 1.0 op_sel_hi:[1,0]
	v_pk_add_f32 v[132:133], v[132:133], 1.0 op_sel_hi:[1,0]
	v_pk_add_f32 v[134:135], v[134:135], 1.0 op_sel_hi:[1,0]
	v_pk_add_f32 v[162:163], v[162:163], 1.0 op_sel_hi:[1,0]
	v_pk_add_f32 v[164:165], v[164:165], 1.0 op_sel_hi:[1,0]
	v_pk_add_f32 v[166:167], v[166:167], 1.0 op_sel_hi:[1,0]
	v_pk_add_f32 v[168:169], v[168:169], 1.0 op_sel_hi:[1,0]
	v_rcp_f32_e32 v128, v128
	v_rcp_f32_e32 v129, v129
	v_rcp_f32_e32 v130, v130
	v_rcp_f32_e32 v131, v131
	v_rcp_f32_e32 v132, v132
	v_rcp_f32_e32 v133, v133
	v_rcp_f32_e32 v134, v134
	v_rcp_f32_e32 v135, v135
	v_rcp_f32_e32 v162, v162
	v_rcp_f32_e32 v163, v163
	v_rcp_f32_e32 v164, v164
	v_rcp_f32_e32 v165, v165
	v_rcp_f32_e32 v166, v166
	v_rcp_f32_e32 v167, v167
	v_rcp_f32_e32 v168, v168
	v_rcp_f32_e32 v169, v169
	v_add_u32_e32 v140, 0x58000, v239
	v_add_u32_e32 v174, 0x84000, v239
	v_pk_mul_f32 v[92:93], v[92:93], v[128:129]
	v_pk_mul_f32 v[94:95], v[94:95], v[130:131]
	v_pk_mul_f32 v[84:85], v[84:85], v[132:133]
	v_pk_mul_f32 v[86:87], v[86:87], v[134:135]
	v_pk_mul_f32 v[76:77], v[76:77], v[162:163]
	v_pk_mul_f32 v[78:79], v[78:79], v[164:165]
	v_pk_mul_f32 v[68:69], v[68:69], v[166:167]
	v_pk_mul_f32 v[70:71], v[70:71], v[168:169]
	v_pk_mul_f32 v[92:93], v[92:93], v[88:89]
	v_pk_mul_f32 v[94:95], v[94:95], v[90:91]
	v_pk_mul_f32 v[84:85], v[84:85], v[80:81]
	v_pk_mul_f32 v[86:87], v[86:87], v[82:83]
	v_pk_mul_f32 v[76:77], v[76:77], v[72:73]
	v_pk_mul_f32 v[78:79], v[78:79], v[74:75]
	v_pk_mul_f32 v[68:69], v[68:69], v[64:65]
	v_pk_mul_f32 v[70:71], v[70:71], v[66:67]
	v_cvt_pk_bf16_f32 v136, v92, v93
	v_cvt_pk_bf16_f32 v137, v94, v95
	v_cvt_pk_bf16_f32 v138, v84, v85
	v_cvt_pk_bf16_f32 v139, v86, v87
	v_cvt_pk_bf16_f32 v170, v76, v77
	v_cvt_pk_bf16_f32 v171, v78, v79
	v_cvt_pk_bf16_f32 v172, v68, v69
	v_cvt_pk_bf16_f32 v173, v70, v71
	global_store_dwordx4 v140, v[136:139], s[28:29]
	global_store_dwordx4 v174, v[170:173], s[28:29]
	s_nop 1
	v_pk_mul_f32 v[60:61], v[60:61], v[228:229] op_sel_hi:[1,0]
	v_pk_mul_f32 v[62:63], v[62:63], v[228:229] op_sel_hi:[1,0]
	v_pk_mul_f32 v[52:53], v[52:53], v[228:229] op_sel_hi:[1,0]
	v_pk_mul_f32 v[54:55], v[54:55], v[228:229] op_sel_hi:[1,0]
	v_pk_mul_f32 v[44:45], v[44:45], v[230:231] op_sel_hi:[1,0]
	v_pk_mul_f32 v[46:47], v[46:47], v[230:231] op_sel_hi:[1,0]
	v_pk_mul_f32 v[36:37], v[36:37], v[230:231] op_sel_hi:[1,0]
	v_pk_mul_f32 v[38:39], v[38:39], v[230:231] op_sel_hi:[1,0]
	v_pk_mul_f32 v[128:129], v[60:61], v[236:237] op_sel_hi:[1,0]
	v_pk_mul_f32 v[130:131], v[62:63], v[236:237] op_sel_hi:[1,0]
	v_pk_mul_f32 v[132:133], v[52:53], v[236:237] op_sel_hi:[1,0]
	v_pk_mul_f32 v[134:135], v[54:55], v[236:237] op_sel_hi:[1,0]
	v_pk_mul_f32 v[162:163], v[44:45], v[236:237] op_sel_hi:[1,0]
	v_pk_mul_f32 v[164:165], v[46:47], v[236:237] op_sel_hi:[1,0]
	v_pk_mul_f32 v[166:167], v[36:37], v[236:237] op_sel_hi:[1,0]
	v_pk_mul_f32 v[168:169], v[38:39], v[236:237] op_sel_hi:[1,0]
	v_exp_f32_e32 v128, v128
	v_exp_f32_e32 v129, v129
	v_exp_f32_e32 v130, v130
	v_exp_f32_e32 v131, v131
	v_exp_f32_e32 v132, v132
	v_exp_f32_e32 v133, v133
	v_exp_f32_e32 v134, v134
	v_exp_f32_e32 v135, v135
	v_exp_f32_e32 v162, v162
	v_exp_f32_e32 v163, v163
	v_exp_f32_e32 v164, v164
	v_exp_f32_e32 v165, v165
	v_exp_f32_e32 v166, v166
	v_exp_f32_e32 v167, v167
	v_exp_f32_e32 v168, v168
	v_exp_f32_e32 v169, v169
	v_pk_mul_f32 v[56:57], v[56:57], v[228:229] op_sel_hi:[1,0]
	v_pk_mul_f32 v[58:59], v[58:59], v[228:229] op_sel_hi:[1,0]
	v_pk_mul_f32 v[48:49], v[48:49], v[228:229] op_sel_hi:[1,0]
	v_pk_mul_f32 v[50:51], v[50:51], v[228:229] op_sel_hi:[1,0]
	v_pk_mul_f32 v[40:41], v[40:41], v[230:231] op_sel_hi:[1,0]
	v_pk_mul_f32 v[42:43], v[42:43], v[230:231] op_sel_hi:[1,0]
	v_pk_mul_f32 v[32:33], v[32:33], v[230:231] op_sel_hi:[1,0]
	v_pk_mul_f32 v[34:35], v[34:35], v[230:231] op_sel_hi:[1,0]
	v_pk_add_f32 v[128:129], v[128:129], 1.0 op_sel_hi:[1,0]
	v_pk_add_f32 v[130:131], v[130:131], 1.0 op_sel_hi:[1,0]
	v_pk_add_f32 v[132:133], v[132:133], 1.0 op_sel_hi:[1,0]
	v_pk_add_f32 v[134:135], v[134:135], 1.0 op_sel_hi:[1,0]
	v_pk_add_f32 v[162:163], v[162:163], 1.0 op_sel_hi:[1,0]
	v_pk_add_f32 v[164:165], v[164:165], 1.0 op_sel_hi:[1,0]
	v_pk_add_f32 v[166:167], v[166:167], 1.0 op_sel_hi:[1,0]
	v_pk_add_f32 v[168:169], v[168:169], 1.0 op_sel_hi:[1,0]
	v_rcp_f32_e32 v128, v128
	v_rcp_f32_e32 v129, v129
	v_rcp_f32_e32 v130, v130
	v_rcp_f32_e32 v131, v131
	v_rcp_f32_e32 v132, v132
	v_rcp_f32_e32 v133, v133
	v_rcp_f32_e32 v134, v134
	v_rcp_f32_e32 v135, v135
	v_rcp_f32_e32 v162, v162
	v_rcp_f32_e32 v163, v163
	v_rcp_f32_e32 v164, v164
	v_rcp_f32_e32 v165, v165
	v_rcp_f32_e32 v166, v166
	v_rcp_f32_e32 v167, v167
	v_rcp_f32_e32 v168, v168
	v_rcp_f32_e32 v169, v169
	v_add_u32_e32 v140, 0x160000, v239
	v_add_u32_e32 v174, 0x18c000, v239
	v_pk_mul_f32 v[60:61], v[60:61], v[128:129]
; __device__ __forceinline__ unsigned cvt_pk_bf16(float lo, float hi) { unsigned r; asm volatile("v_cvt_pk_bf16_f32 %0, %1, %2" : "=v"(r) : "v"(lo), "v"(hi)); return r; }
; __device__ __forceinline__ float sigmoidf_(float x) { return fast_rcp(1.0f + fast_exp2(-1.4426950408889634f * x)); }
; #define PG8_BAR __builtin_amdgcn_s_barrier()
;     __device__ __forceinline__ void operator()(const f32x4 (&acc)[2][2][4][2], const Unit& u, int wr, int wc, int fr, int fq) const {
;     ...
;             for (int m = 0; m < 4; ++m) { const float sc = rs[ai][m]; f32x4 o[2];
; #pragma unroll
;                 for (int n = 0; n < 2; ++n) { const f32x4 g = acc[ai][0][m][n] * sc, up = acc[ai][1][m][n] * sc;
; #pragma unroll
;                     for (int e = 0; e < 4; ++e) o[n][e] = g[e] * sigmoidf_(g[e]) * up[e]; }
;                 u32x4 w; w.x = cvt_pk_bf16(o[0][0], o[0][1]); w.y = cvt_pk_bf16(o[0][2], o[0][3]); w.z = cvt_pk_bf16(o[1][0], o[1][1]); w.w = cvt_pk_bf16(o[1][2], o[1][3]);
;                 *(u32x4*)(O + (size_t)(row0 + ai * HALF + m * 16) * FF + col0) = w; }
; template <class Epi, class Sched, bool ALIGN_EPI>
; __device__ __forceinline__ void gemm_phase(LAS unsigned char* lds, const Gemm g, const Sched& S, const Epi& E) {
;     ...
;         if (!has_next) break;
; #pragma unroll
;         for (int a = 0; a < 2; ++a)
; #pragma unroll
;             for (int b = 0; b < 2; ++b)
; #pragma unroll
;                 for (int m = 0; m < 4; ++m)
; #pragma unroll
;                     for (int n = 0; n < 2; ++n) acc[a][b][m][n] = (f32x4){0.f, 0.f, 0.f, 0.f};
;         cur = nxt; cA = nA; cB = nB; ++ui;
;         if constexpr (ALIGN_EPI) { if (wr == 1) PG8_BAR; }
	v_pk_mul_f32 v[62:63], v[62:63], v[130:131]
	v_pk_mul_f32 v[52:53], v[52:53], v[132:133]
	v_pk_mul_f32 v[54:55], v[54:55], v[134:135]
	v_pk_mul_f32 v[44:45], v[44:45], v[162:163]
	v_pk_mul_f32 v[46:47], v[46:47], v[164:165]
	v_pk_mul_f32 v[36:37], v[36:37], v[166:167]
	v_pk_mul_f32 v[38:39], v[38:39], v[168:169]
	v_pk_mul_f32 v[60:61], v[60:61], v[56:57]
	v_pk_mul_f32 v[62:63], v[62:63], v[58:59]
	v_pk_mul_f32 v[52:53], v[52:53], v[48:49]
	v_pk_mul_f32 v[54:55], v[54:55], v[50:51]
	v_pk_mul_f32 v[44:45], v[44:45], v[40:41]
	v_pk_mul_f32 v[46:47], v[46:47], v[42:43]
	v_pk_mul_f32 v[36:37], v[36:37], v[32:33]
	v_pk_mul_f32 v[38:39], v[38:39], v[34:35]
	v_cvt_pk_bf16_f32 v136, v60, v61
	v_cvt_pk_bf16_f32 v137, v62, v63
	v_cvt_pk_bf16_f32 v138, v52, v53
	v_cvt_pk_bf16_f32 v139, v54, v55
	v_cvt_pk_bf16_f32 v170, v44, v45
	v_cvt_pk_bf16_f32 v171, v46, v47
	v_cvt_pk_bf16_f32 v172, v36, v37
	v_cvt_pk_bf16_f32 v173, v38, v39
	global_store_dwordx4 v140, v[136:139], s[28:29]
	global_store_dwordx4 v174, v[170:173], s[28:29]
	s_nop 1
	v_pk_mul_f32 v[28:29], v[28:29], v[232:233] op_sel_hi:[1,0]
	v_pk_mul_f32 v[30:31], v[30:31], v[232:233] op_sel_hi:[1,0]
	v_pk_mul_f32 v[20:21], v[20:21], v[232:233] op_sel_hi:[1,0]
	v_pk_mul_f32 v[22:23], v[22:23], v[232:233] op_sel_hi:[1,0]
	v_pk_mul_f32 v[12:13], v[12:13], v[234:235] op_sel_hi:[1,0]
	v_pk_mul_f32 v[14:15], v[14:15], v[234:235] op_sel_hi:[1,0]
	v_pk_mul_f32 v[4:5], v[4:5], v[234:235] op_sel_hi:[1,0]
	v_pk_mul_f32 v[6:7], v[6:7], v[234:235] op_sel_hi:[1,0]
	v_pk_mul_f32 v[128:129], v[28:29], v[236:237] op_sel_hi:[1,0]
	v_pk_mul_f32 v[130:131], v[30:31], v[236:237] op_sel_hi:[1,0]
	v_pk_mul_f32 v[132:133], v[20:21], v[236:237] op_sel_hi:[1,0]
	v_pk_mul_f32 v[134:135], v[22:23], v[236:237] op_sel_hi:[1,0]
	v_pk_mul_f32 v[162:163], v[12:13], v[236:237] op_sel_hi:[1,0]
	v_pk_mul_f32 v[164:165], v[14:15], v[236:237] op_sel_hi:[1,0]
	v_pk_mul_f32 v[166:167], v[4:5], v[236:237] op_sel_hi:[1,0]
	v_pk_mul_f32 v[168:169], v[6:7], v[236:237] op_sel_hi:[1,0]
	v_exp_f32_e32 v128, v128
	v_exp_f32_e32 v129, v129
	v_exp_f32_e32 v130, v130
	v_exp_f32_e32 v131, v131
	v_exp_f32_e32 v132, v132
	v_exp_f32_e32 v133, v133
	v_exp_f32_e32 v134, v134
	v_exp_f32_e32 v135, v135
	v_exp_f32_e32 v162, v162
	v_exp_f32_e32 v163, v163
	v_exp_f32_e32 v164, v164
	v_exp_f32_e32 v165, v165
	v_exp_f32_e32 v166, v166
	v_exp_f32_e32 v167, v167
	v_exp_f32_e32 v168, v168
	v_exp_f32_e32 v169, v169
	v_pk_mul_f32 v[24:25], v[24:25], v[232:233] op_sel_hi:[1,0]
	v_pk_mul_f32 v[26:27], v[26:27], v[232:233] op_sel_hi:[1,0]
	v_pk_mul_f32 v[16:17], v[16:17], v[232:233] op_sel_hi:[1,0]
	v_pk_mul_f32 v[18:19], v[18:19], v[232:233] op_sel_hi:[1,0]
	v_pk_mul_f32 v[8:9], v[8:9], v[234:235] op_sel_hi:[1,0]
	v_pk_mul_f32 v[10:11], v[10:11], v[234:235] op_sel_hi:[1,0]
	v_pk_mul_f32 v[0:1], v[0:1], v[234:235] op_sel_hi:[1,0]
	v_pk_mul_f32 v[2:3], v[2:3], v[234:235] op_sel_hi:[1,0]
	v_pk_add_f32 v[128:129], v[128:129], 1.0 op_sel_hi:[1,0]
	v_pk_add_f32 v[130:131], v[130:131], 1.0 op_sel_hi:[1,0]
	v_pk_add_f32 v[132:133], v[132:133], 1.0 op_sel_hi:[1,0]
	v_pk_add_f32 v[134:135], v[134:135], 1.0 op_sel_hi:[1,0]
	v_pk_add_f32 v[162:163], v[162:163], 1.0 op_sel_hi:[1,0]
	v_pk_add_f32 v[164:165], v[164:165], 1.0 op_sel_hi:[1,0]
	v_pk_add_f32 v[166:167], v[166:167], 1.0 op_sel_hi:[1,0]
	v_pk_add_f32 v[168:169], v[168:169], 1.0 op_sel_hi:[1,0]
	v_rcp_f32_e32 v128, v128
	v_rcp_f32_e32 v129, v129
	v_rcp_f32_e32 v130, v130
	v_rcp_f32_e32 v131, v131
	v_rcp_f32_e32 v132, v132
	v_rcp_f32_e32 v133, v133
	v_rcp_f32_e32 v134, v134
	v_rcp_f32_e32 v135, v135
	v_rcp_f32_e32 v162, v162
	v_rcp_f32_e32 v163, v163
	v_rcp_f32_e32 v164, v164
	v_rcp_f32_e32 v165, v165
	v_rcp_f32_e32 v166, v166
	v_rcp_f32_e32 v167, v167
	v_rcp_f32_e32 v168, v168
	v_rcp_f32_e32 v169, v169
	v_add_u32_e32 v140, 0x1b8000, v239
	v_add_u32_e32 v174, 0x1e4000, v239
	v_pk_mul_f32 v[28:29], v[28:29], v[128:129]
	v_pk_mul_f32 v[30:31], v[30:31], v[130:131]
	v_pk_mul_f32 v[20:21], v[20:21], v[132:133]
	v_pk_mul_f32 v[22:23], v[22:23], v[134:135]
	v_pk_mul_f32 v[12:13], v[12:13], v[162:163]
	v_pk_mul_f32 v[14:15], v[14:15], v[164:165]
	v_pk_mul_f32 v[4:5], v[4:5], v[166:167]
	v_pk_mul_f32 v[6:7], v[6:7], v[168:169]
	v_pk_mul_f32 v[28:29], v[28:29], v[24:25]
	v_pk_mul_f32 v[30:31], v[30:31], v[26:27]
	v_pk_mul_f32 v[20:21], v[20:21], v[16:17]
	v_pk_mul_f32 v[22:23], v[22:23], v[18:19]
	v_pk_mul_f32 v[12:13], v[12:13], v[8:9]
	v_pk_mul_f32 v[14:15], v[14:15], v[10:11]
	v_pk_mul_f32 v[4:5], v[4:5], v[0:1]
	v_pk_mul_f32 v[6:7], v[6:7], v[2:3]
	v_cvt_pk_bf16_f32 v136, v28, v29
	v_cvt_pk_bf16_f32 v137, v30, v31
	v_cvt_pk_bf16_f32 v138, v20, v21
	v_cvt_pk_bf16_f32 v139, v22, v23
	v_cvt_pk_bf16_f32 v170, v12, v13
	v_cvt_pk_bf16_f32 v171, v14, v15
	v_cvt_pk_bf16_f32 v172, v4, v5
	v_cvt_pk_bf16_f32 v173, v6, v7
	global_store_dwordx4 v140, v[136:139], s[28:29]
	global_store_dwordx4 v174, v[170:173], s[28:29]
	s_andn2_b64 vcc, exec, s[2:3]
	s_mov_b64 s[2:3], -1
	s_cbranch_vccnz .LBB0_1144
	s_andn2_b64 vcc, exec, s[24:25]
	s_cbranch_vccnz .LBB0_1143
	s_barrier
	s_branch .LBB0_1143

; __global__ void __launch_bounds__(NTHR, 2) fwd_megakernel(Args args) {
	.amdhsa_kernel _Z14fwd_megakernel4Args
		.amdhsa_group_segment_fixed_size 0
		.amdhsa_private_segment_fixed_size 0
		.amdhsa_kernarg_size 504
		.amdhsa_user_sgpr_count 2
		.amdhsa_user_sgpr_dispatch_ptr 0
		.amdhsa_user_sgpr_queue_ptr 0
		.amdhsa_user_sgpr_kernarg_segment_ptr 1
		.amdhsa_user_sgpr_dispatch_id 0
		.amdhsa_user_sgpr_kernarg_preload_length 0
		.amdhsa_user_sgpr_kernarg_preload_offset 0
		.amdhsa_user_sgpr_private_segment_size 0
		.amdhsa_uses_dynamic_stack 0
		.amdhsa_enable_private_segment 0
		.amdhsa_system_sgpr_workgroup_id_x 1
		.amdhsa_system_sgpr_workgroup_id_y 0
		.amdhsa_system_sgpr_workgroup_id_z 0
		.amdhsa_system_sgpr_workgroup_info 0
		.amdhsa_system_vgpr_workitem_id 2
		.amdhsa_next_free_vgpr 255
		.amdhsa_next_free_sgpr 102
		.amdhsa_accum_offset 256
		.amdhsa_reserve_vcc 1
		.amdhsa_float_round_mode_32 0
		.amdhsa_float_round_mode_16_64 0
		.amdhsa_float_denorm_mode_32 3
		.amdhsa_float_denorm_mode_16_64 3
		.amdhsa_dx10_clamp 1
		.amdhsa_ieee_mode 1
		.amdhsa_fp16_overflow 0
		.amdhsa_tg_split 0
		.amdhsa_exception_fp_ieee_invalid_op 0
		.amdhsa_exception_fp_denorm_src 0
		.amdhsa_exception_fp_ieee_div_zero 0
		.amdhsa_exception_fp_ieee_overflow 0
		.amdhsa_exception_fp_ieee_underflow 0
		.amdhsa_exception_fp_ieee_inexact 0
		.amdhsa_exception_int_div_zero 0
	.end_amdhsa_kernel

; __global__ void __launch_bounds__(NTHR, 2) fwd_megakernel(Args args) {
amdhsa.kernels:
  - .agpr_count:     0
    .args:
      - .offset:         0
        .size:           248
        .value_kind:     by_value
      - .offset:         248
        .size:           4
        .value_kind:     hidden_block_count_x
      - .offset:         252
        .size:           4
        .value_kind:     hidden_block_count_y
      - .offset:         256
        .size:           4
        .value_kind:     hidden_block_count_z
      - .offset:         260
        .size:           2
        .value_kind:     hidden_group_size_x
      - .offset:         262
        .size:           2
        .value_kind:     hidden_group_size_y
      - .offset:         264
        .size:           2
        .value_kind:     hidden_group_size_z
      - .offset:         266
        .size:           2
        .value_kind:     hidden_remainder_x
      - .offset:         268
        .size:           2
        .value_kind:     hidden_remainder_y
      - .offset:         270
        .size:           2
        .value_kind:     hidden_remainder_z
      - .offset:         288
        .size:           8
        .value_kind:     hidden_global_offset_x
      - .offset:         296
        .size:           8
        .value_kind:     hidden_global_offset_y
      - .offset:         304
        .size:           8
        .value_kind:     hidden_global_offset_z
      - .offset:         312
        .size:           2
        .value_kind:     hidden_grid_dims
      - .offset:         336
        .size:           8
        .value_kind:     hidden_multigrid_sync_arg
      - .offset:         368
        .size:           4
        .value_kind:     hidden_dynamic_lds_size
    .group_segment_fixed_size: 0
    .kernarg_segment_align: 8
    .kernarg_segment_size: 504
    .language:       OpenCL C
    .language_version:
      - 2
      - 0
    .max_flat_workgroup_size: 512
    .name:           _Z14fwd_megakernel4Args
    .private_segment_fixed_size: 0
    .sgpr_count:     108
    .sgpr_spill_count: 11
    .symbol:         _Z14fwd_megakernel4Args.kd
    .uniform_work_group_size: 1
    .uses_dynamic_stack: false
    .vgpr_count:     255
    .vgpr_spill_count: 0
    .wavefront_size: 64
